# vp56 plus two 4-byte nops inside the P8 K-loop load segments so all eight MFMA blocks start at 4 mod 8
# speedup vs baseline: 1.0016x; 1.0016x over previous
.LBB0_723:
	ds_read_b128 v[154:157], v149
	ds_read_b128 v[158:161], v149 offset:1024
	ds_read_b128 v[162:165], v149 offset:2048
	ds_read_b128 v[166:169], v149 offset:3072
	ds_read_b128 v[170:173], v150
	ds_read_b128 v[174:177], v150 offset:1024
	ds_read_b128 v[178:181], v150 offset:2048
	ds_read_b128 v[182:185], v150 offset:3072
	s_add_u32 s30, s28, 0xfff80080
	s_addc_u32 s31, s29, -1
	s_cmp_eq_u32 s59, 28
	s_cselect_b32 s35, s1, s31
	s_cselect_b32 s34, s9, s30
	s_cselect_b32 s31, s19, s33
	s_cselect_b32 s30, s21, s27
	v_lshl_add_u64 v[144:145], s[28:29], 0, v[136:137]
	s_add_i32 m0, s47, 0xc000
	ds_read_b128 v[186:189], v151
	ds_read_b128 v[190:193], v151 offset:1024
	ds_read_b128 v[194:197], v151 offset:2048
	ds_read_b128 v[198:201], v151 offset:3072
	ds_read_b128 v[202:205], v151 offset:4096
	ds_read_b128 v[206:209], v151 offset:5120
	ds_read_b128 v[210:213], v151 offset:6144
	ds_read_b128 v[214:217], v151 offset:7168
	global_load_lds_dwordx4 v[144:145], off
	v_lshl_add_u64 v[144:145], s[28:29], 0, v[138:139]
	s_add_i32 m0, s47, 0xe000
	s_nop 0
	global_load_lds_dwordx4 v[144:145], off
	s_waitcnt vmcnt(8)
	s_waitcnt lgkmcnt(0)
	s_barrier
	s_setprio 1
	s_waitcnt lgkmcnt(0)
	v_mfma_f32_16x16x32_bf16 v[124:127], v[154:157], v[186:189], v[124:127]
	v_mfma_f32_16x16x32_bf16 v[120:123], v[162:165], v[186:189], v[120:123]
	v_mfma_f32_16x16x32_bf16 v[108:111], v[154:157], v[194:197], v[108:111]
	v_mfma_f32_16x16x32_bf16 v[104:107], v[162:165], v[194:197], v[104:107]
	v_mfma_f32_16x16x32_bf16 v[92:95], v[154:157], v[202:205], v[92:95]
	v_mfma_f32_16x16x32_bf16 v[88:91], v[162:165], v[202:205], v[88:91]
	v_mfma_f32_16x16x32_bf16 v[76:79], v[154:157], v[210:213], v[76:79]
	v_mfma_f32_16x16x32_bf16 v[72:75], v[162:165], v[210:213], v[72:75]
	v_mfma_f32_16x16x32_bf16 v[124:127], v[158:161], v[190:193], v[124:127]
	v_mfma_f32_16x16x32_bf16 v[120:123], v[166:169], v[190:193], v[120:123]
	v_mfma_f32_16x16x32_bf16 v[108:111], v[158:161], v[198:201], v[108:111]
	v_mfma_f32_16x16x32_bf16 v[104:107], v[166:169], v[198:201], v[104:107]
	v_mfma_f32_16x16x32_bf16 v[92:95], v[158:161], v[206:209], v[92:95]
	v_mfma_f32_16x16x32_bf16 v[88:91], v[166:169], v[206:209], v[88:91]
	v_mfma_f32_16x16x32_bf16 v[76:79], v[158:161], v[214:217], v[76:79]
	v_mfma_f32_16x16x32_bf16 v[72:75], v[166:169], v[214:217], v[72:75]
	s_setprio 0
	s_setprio 1
	v_mfma_f32_16x16x32_bf16 v[116:119], v[170:173], v[186:189], v[116:119]
	v_mfma_f32_16x16x32_bf16 v[112:115], v[178:181], v[186:189], v[112:115]
	v_mfma_f32_16x16x32_bf16 v[100:103], v[170:173], v[194:197], v[100:103]
	v_mfma_f32_16x16x32_bf16 v[96:99], v[178:181], v[194:197], v[96:99]
	v_mfma_f32_16x16x32_bf16 v[84:87], v[170:173], v[202:205], v[84:87]
	v_mfma_f32_16x16x32_bf16 v[80:83], v[178:181], v[202:205], v[80:83]
	v_mfma_f32_16x16x32_bf16 v[68:71], v[170:173], v[210:213], v[68:71]
	v_mfma_f32_16x16x32_bf16 v[64:67], v[178:181], v[210:213], v[64:67]
	v_mfma_f32_16x16x32_bf16 v[116:119], v[174:177], v[190:193], v[116:119]
	v_mfma_f32_16x16x32_bf16 v[112:115], v[182:185], v[190:193], v[112:115]
	v_mfma_f32_16x16x32_bf16 v[100:103], v[174:177], v[198:201], v[100:103]
	v_mfma_f32_16x16x32_bf16 v[96:99], v[182:185], v[198:201], v[96:99]
	v_mfma_f32_16x16x32_bf16 v[84:87], v[174:177], v[206:209], v[84:87]
	v_mfma_f32_16x16x32_bf16 v[80:83], v[182:185], v[206:209], v[80:83]
	v_mfma_f32_16x16x32_bf16 v[68:71], v[174:177], v[214:217], v[68:71]
	v_mfma_f32_16x16x32_bf16 v[64:67], v[182:185], v[214:217], v[64:67]
	s_setprio 0
	s_barrier
	s_add_i32 s60, s56, s46
	v_lshl_add_u64 v[144:145], s[30:31], 0, v[130:131]
	s_mov_b32 m0, s60
	ds_read_b128 v[186:189], v151 offset:16384
	ds_read_b128 v[190:193], v151 offset:17408
	ds_read_b128 v[194:197], v151 offset:18432
	ds_read_b128 v[198:201], v151 offset:19456
	ds_read_b128 v[202:205], v151 offset:20480
	ds_read_b128 v[206:209], v151 offset:21504
	ds_read_b128 v[210:213], v151 offset:22528
	ds_read_b128 v[214:217], v151 offset:23552
	global_load_lds_dwordx4 v[144:145], off
	s_add_i32 m0, s60, 0x2000
	s_add_u32 s60, s30, 0x80000
	v_lshl_add_u64 v[218:219], s[30:31], 0, v[134:135]
	s_addc_u32 s61, s31, 0
	s_add_i32 s62, s57, s46
	global_load_lds_dwordx4 v[218:219], off
	v_lshl_add_u64 v[220:221], s[60:61], 0, v[130:131]
	s_mov_b32 m0, s62
	v_lshl_add_u64 v[222:223], s[34:35], 0, v[132:133]
	global_load_lds_dwordx4 v[220:221], off
	v_lshl_add_u64 v[220:221], s[60:61], 0, v[134:135]
	s_add_i32 m0, s62, 0x2000
	s_nop 0
	global_load_lds_dwordx4 v[220:221], off
	v_lshl_add_u64 v[220:221], s[34:35], 0, v[128:129]
	s_mov_b32 m0, s47
	s_nop 0
	global_load_lds_dwordx4 v[220:221], off
	s_mov_b32 m0, s36
	s_nop 0
	global_load_lds_dwordx4 v[222:223], off
	s_nop 0
	s_waitcnt vmcnt(8)
	s_waitcnt lgkmcnt(0)
	s_barrier
	s_setprio 1
	s_waitcnt lgkmcnt(0)
	v_mfma_f32_16x16x32_bf16 v[60:63], v[154:157], v[186:189], v[60:63]
	v_mfma_f32_16x16x32_bf16 v[56:59], v[162:165], v[186:189], v[56:59]
	v_mfma_f32_16x16x32_bf16 v[44:47], v[154:157], v[194:197], v[44:47]
	v_mfma_f32_16x16x32_bf16 v[40:43], v[162:165], v[194:197], v[40:43]
	v_mfma_f32_16x16x32_bf16 v[28:31], v[154:157], v[202:205], v[28:31]
	v_mfma_f32_16x16x32_bf16 v[24:27], v[162:165], v[202:205], v[24:27]
	v_mfma_f32_16x16x32_bf16 v[12:15], v[154:157], v[210:213], v[12:15]
	v_mfma_f32_16x16x32_bf16 v[8:11], v[162:165], v[210:213], v[8:11]
	v_mfma_f32_16x16x32_bf16 v[60:63], v[158:161], v[190:193], v[60:63]
	v_mfma_f32_16x16x32_bf16 v[56:59], v[166:169], v[190:193], v[56:59]
	v_mfma_f32_16x16x32_bf16 v[44:47], v[158:161], v[198:201], v[44:47]
	v_mfma_f32_16x16x32_bf16 v[40:43], v[166:169], v[198:201], v[40:43]
	v_mfma_f32_16x16x32_bf16 v[28:31], v[158:161], v[206:209], v[28:31]
	v_mfma_f32_16x16x32_bf16 v[24:27], v[166:169], v[206:209], v[24:27]
	v_mfma_f32_16x16x32_bf16 v[12:15], v[158:161], v[214:217], v[12:15]
	v_mfma_f32_16x16x32_bf16 v[8:11], v[166:169], v[214:217], v[8:11]
	s_setprio 0
	s_setprio 1
	v_mfma_f32_16x16x32_bf16 v[52:55], v[170:173], v[186:189], v[52:55]
	v_mfma_f32_16x16x32_bf16 v[48:51], v[178:181], v[186:189], v[48:51]
	v_mfma_f32_16x16x32_bf16 v[36:39], v[170:173], v[194:197], v[36:39]
	v_mfma_f32_16x16x32_bf16 v[32:35], v[178:181], v[194:197], v[32:35]
	v_mfma_f32_16x16x32_bf16 v[20:23], v[170:173], v[202:205], v[20:23]
	v_mfma_f32_16x16x32_bf16 v[16:19], v[178:181], v[202:205], v[16:19]
	v_mfma_f32_16x16x32_bf16 v[4:7], v[170:173], v[210:213], v[4:7]
	v_mfma_f32_16x16x32_bf16 v[0:3], v[178:181], v[210:213], v[0:3]
	v_mfma_f32_16x16x32_bf16 v[52:55], v[174:177], v[190:193], v[52:55]
	v_mfma_f32_16x16x32_bf16 v[48:51], v[182:185], v[190:193], v[48:51]
	v_mfma_f32_16x16x32_bf16 v[36:39], v[174:177], v[198:201], v[36:39]
	v_mfma_f32_16x16x32_bf16 v[32:35], v[182:185], v[198:201], v[32:35]
	v_mfma_f32_16x16x32_bf16 v[20:23], v[174:177], v[206:209], v[20:23]
	v_mfma_f32_16x16x32_bf16 v[16:19], v[182:185], v[206:209], v[16:19]
	v_mfma_f32_16x16x32_bf16 v[4:7], v[174:177], v[214:217], v[4:7]
	v_mfma_f32_16x16x32_bf16 v[0:3], v[182:185], v[214:217], v[0:3]
	s_setprio 0
	s_barrier
	s_add_i32 s60, 0, 0x18000
	v_add_u32_e32 v153, s60, v147
	s_add_i32 s61, 0, 0x1c000
	ds_read_b128 v[154:157], v153
	ds_read_b128 v[158:161], v153 offset:1024
	ds_read_b128 v[162:165], v153 offset:2048
	ds_read_b128 v[166:169], v153 offset:3072
	v_add_u32_e32 v153, s61, v147
	ds_read_b128 v[170:173], v153
	ds_read_b128 v[174:177], v153 offset:1024
	ds_read_b128 v[178:181], v153 offset:2048
	ds_read_b128 v[182:185], v153 offset:3072
	s_add_u32 s34, s34, 0x80000
	s_addc_u32 s35, s35, 0
	s_mov_b32 m0, s37
	v_lshl_add_u64 v[224:225], s[34:35], 0, v[128:129]
	ds_read_b128 v[186:189], v151 offset:32768
	ds_read_b128 v[190:193], v151 offset:33792
	ds_read_b128 v[194:197], v151 offset:34816
	ds_read_b128 v[198:201], v151 offset:35840
	ds_read_b128 v[202:205], v151 offset:36864
	ds_read_b128 v[206:209], v151 offset:37888
	ds_read_b128 v[210:213], v151 offset:38912
	ds_read_b128 v[214:217], v151 offset:39936
	global_load_lds_dwordx4 v[224:225], off
	v_lshl_add_u64 v[224:225], s[34:35], 0, v[132:133]
	s_mov_b32 m0, s48
	s_nop 0
	global_load_lds_dwordx4 v[224:225], off
	s_nop 0
	s_waitcnt vmcnt(8)
	s_waitcnt lgkmcnt(0)
	s_barrier
	s_setprio 1
	s_waitcnt lgkmcnt(0)
	v_mfma_f32_16x16x32_bf16 v[124:127], v[154:157], v[186:189], v[124:127]
	v_mfma_f32_16x16x32_bf16 v[120:123], v[162:165], v[186:189], v[120:123]
	v_mfma_f32_16x16x32_bf16 v[108:111], v[154:157], v[194:197], v[108:111]
	v_mfma_f32_16x16x32_bf16 v[104:107], v[162:165], v[194:197], v[104:107]
	v_mfma_f32_16x16x32_bf16 v[92:95], v[154:157], v[202:205], v[92:95]
	v_mfma_f32_16x16x32_bf16 v[88:91], v[162:165], v[202:205], v[88:91]
	v_mfma_f32_16x16x32_bf16 v[76:79], v[154:157], v[210:213], v[76:79]
	v_mfma_f32_16x16x32_bf16 v[72:75], v[162:165], v[210:213], v[72:75]
	v_mfma_f32_16x16x32_bf16 v[124:127], v[158:161], v[190:193], v[124:127]
	v_mfma_f32_16x16x32_bf16 v[120:123], v[166:169], v[190:193], v[120:123]
	v_mfma_f32_16x16x32_bf16 v[108:111], v[158:161], v[198:201], v[108:111]
	v_mfma_f32_16x16x32_bf16 v[104:107], v[166:169], v[198:201], v[104:107]
	v_mfma_f32_16x16x32_bf16 v[92:95], v[158:161], v[206:209], v[92:95]
	v_mfma_f32_16x16x32_bf16 v[88:91], v[166:169], v[206:209], v[88:91]
	v_mfma_f32_16x16x32_bf16 v[76:79], v[158:161], v[214:217], v[76:79]
	v_mfma_f32_16x16x32_bf16 v[72:75], v[166:169], v[214:217], v[72:75]
	s_setprio 0
	s_setprio 1
	v_mfma_f32_16x16x32_bf16 v[116:119], v[170:173], v[186:189], v[116:119]
	v_mfma_f32_16x16x32_bf16 v[112:115], v[178:181], v[186:189], v[112:115]
	v_mfma_f32_16x16x32_bf16 v[100:103], v[170:173], v[194:197], v[100:103]
	v_mfma_f32_16x16x32_bf16 v[96:99], v[178:181], v[194:197], v[96:99]
	v_mfma_f32_16x16x32_bf16 v[84:87], v[170:173], v[202:205], v[84:87]
	v_mfma_f32_16x16x32_bf16 v[80:83], v[178:181], v[202:205], v[80:83]
	v_mfma_f32_16x16x32_bf16 v[68:71], v[170:173], v[210:213], v[68:71]
	v_mfma_f32_16x16x32_bf16 v[64:67], v[178:181], v[210:213], v[64:67]
	v_mfma_f32_16x16x32_bf16 v[116:119], v[174:177], v[190:193], v[116:119]
	v_mfma_f32_16x16x32_bf16 v[112:115], v[182:185], v[190:193], v[112:115]
	v_mfma_f32_16x16x32_bf16 v[100:103], v[174:177], v[198:201], v[100:103]
	v_mfma_f32_16x16x32_bf16 v[96:99], v[182:185], v[198:201], v[96:99]
	v_mfma_f32_16x16x32_bf16 v[84:87], v[174:177], v[206:209], v[84:87]
	v_mfma_f32_16x16x32_bf16 v[80:83], v[182:185], v[206:209], v[80:83]
	v_mfma_f32_16x16x32_bf16 v[68:71], v[174:177], v[214:217], v[68:71]
	v_mfma_f32_16x16x32_bf16 v[64:67], v[182:185], v[214:217], v[64:67]
	s_setprio 0
	s_barrier
; #define PG8_BAR __builtin_amdgcn_s_barrier()
; template <class Epi, class Sched, bool ALIGN_EPI = false, bool SP2 = false, bool FP8 = false, bool MIX8 = false>
; __device__ __forceinline__ void gemm_phase(PG8_LAS unsigned char* lds, const Gemm g, const Sched& S, const Epi& E) {
;     ...
;         for (int t = 0; t < nt; t += 2) {
;     ...
;         if constexpr (ALIGN_EPI) { if (wr == 0) PG8_BAR; }
	s_add_i32 s34, s60, s46
	v_lshl_add_u64 v[144:145], v[144:145], 0, s[14:15]
	s_mov_b32 m0, s34
	ds_read_b128 v[186:189], v151 offset:49152
	ds_read_b128 v[190:193], v151 offset:50176
	ds_read_b128 v[194:197], v151 offset:51200
	ds_read_b128 v[198:201], v151 offset:52224
	ds_read_b128 v[202:205], v151 offset:53248
	ds_read_b128 v[206:209], v151 offset:54272
	ds_read_b128 v[210:213], v151 offset:55296
	ds_read_b128 v[214:217], v151 offset:56320
	global_load_lds_dwordx4 v[144:145], off
	s_add_i32 m0, s34, 0x2000
	s_add_u32 s30, s30, 0x80080
	v_lshl_add_u64 v[144:145], v[218:219], 0, s[14:15]
	s_addc_u32 s31, s31, 0
	s_add_i32 s34, s61, s46
	global_load_lds_dwordx4 v[144:145], off
	v_lshl_add_u64 v[144:145], s[30:31], 0, v[130:131]
	s_mov_b32 m0, s34
	s_nop 0
	global_load_lds_dwordx4 v[144:145], off
	v_lshl_add_u64 v[144:145], s[30:31], 0, v[134:135]
	s_add_i32 m0, s34, 0x2000
	s_nop 0
	global_load_lds_dwordx4 v[144:145], off
	v_lshl_add_u64 v[144:145], v[220:221], 0, s[14:15]
	s_mov_b32 m0, s50
	s_nop 0
	global_load_lds_dwordx4 v[144:145], off
	v_lshl_add_u64 v[144:145], v[222:223], 0, s[14:15]
	s_mov_b32 m0, s51
	s_nop 0
	global_load_lds_dwordx4 v[144:145], off
	s_waitcnt vmcnt(8)
	s_waitcnt lgkmcnt(0)
	s_barrier
	s_setprio 1
	s_waitcnt lgkmcnt(0)
	v_mfma_f32_16x16x32_bf16 v[60:63], v[154:157], v[186:189], v[60:63]
	v_mfma_f32_16x16x32_bf16 v[56:59], v[162:165], v[186:189], v[56:59]
	v_mfma_f32_16x16x32_bf16 v[44:47], v[154:157], v[194:197], v[44:47]
	v_mfma_f32_16x16x32_bf16 v[40:43], v[162:165], v[194:197], v[40:43]
	v_mfma_f32_16x16x32_bf16 v[28:31], v[154:157], v[202:205], v[28:31]
	v_mfma_f32_16x16x32_bf16 v[24:27], v[162:165], v[202:205], v[24:27]
	v_mfma_f32_16x16x32_bf16 v[12:15], v[154:157], v[210:213], v[12:15]
	v_mfma_f32_16x16x32_bf16 v[8:11], v[162:165], v[210:213], v[8:11]
	v_mfma_f32_16x16x32_bf16 v[60:63], v[158:161], v[190:193], v[60:63]
	v_mfma_f32_16x16x32_bf16 v[56:59], v[166:169], v[190:193], v[56:59]
	v_mfma_f32_16x16x32_bf16 v[44:47], v[158:161], v[198:201], v[44:47]
	v_mfma_f32_16x16x32_bf16 v[40:43], v[166:169], v[198:201], v[40:43]
	v_mfma_f32_16x16x32_bf16 v[28:31], v[158:161], v[206:209], v[28:31]
	v_mfma_f32_16x16x32_bf16 v[24:27], v[166:169], v[206:209], v[24:27]
	v_mfma_f32_16x16x32_bf16 v[12:15], v[158:161], v[214:217], v[12:15]
	v_mfma_f32_16x16x32_bf16 v[8:11], v[166:169], v[214:217], v[8:11]
	s_setprio 0
	s_setprio 1
	v_mfma_f32_16x16x32_bf16 v[52:55], v[170:173], v[186:189], v[52:55]
	v_mfma_f32_16x16x32_bf16 v[48:51], v[178:181], v[186:189], v[48:51]
	v_mfma_f32_16x16x32_bf16 v[36:39], v[170:173], v[194:197], v[36:39]
	v_mfma_f32_16x16x32_bf16 v[32:35], v[178:181], v[194:197], v[32:35]
	v_mfma_f32_16x16x32_bf16 v[20:23], v[170:173], v[202:205], v[20:23]
	v_mfma_f32_16x16x32_bf16 v[16:19], v[178:181], v[202:205], v[16:19]
	v_mfma_f32_16x16x32_bf16 v[4:7], v[170:173], v[210:213], v[4:7]
	v_mfma_f32_16x16x32_bf16 v[0:3], v[178:181], v[210:213], v[0:3]
	v_mfma_f32_16x16x32_bf16 v[52:55], v[174:177], v[190:193], v[52:55]
	v_mfma_f32_16x16x32_bf16 v[48:51], v[182:185], v[190:193], v[48:51]
	v_mfma_f32_16x16x32_bf16 v[36:39], v[174:177], v[198:201], v[36:39]
	v_mfma_f32_16x16x32_bf16 v[32:35], v[182:185], v[198:201], v[32:35]
	v_mfma_f32_16x16x32_bf16 v[20:23], v[174:177], v[206:209], v[20:23]
	v_mfma_f32_16x16x32_bf16 v[16:19], v[182:185], v[206:209], v[16:19]
	v_mfma_f32_16x16x32_bf16 v[4:7], v[174:177], v[214:217], v[4:7]
	v_mfma_f32_16x16x32_bf16 v[0:3], v[182:185], v[214:217], v[0:3]
	s_setprio 0
	s_barrier
	s_add_i32 s59, s59, 2
	s_add_u32 s28, s28, 0x100
	s_addc_u32 s29, s29, 0
	s_add_u32 s27, s27, 0x100
	s_addc_u32 s33, s33, 0
	s_cmp_gt_u32 s59, 29
	s_cbranch_scc0 .LBB0_723
	s_and_b64 vcc, exec, s[16:17]
	s_cbranch_vccz .LBB0_726
	s_barrier

; __device__ __forceinline__ void xcd_barrier(const XcdBarrier& b) {
;     ...
;     }
;     __syncthreads();
.LBB0_814:
	s_or_b64 exec, exec, s[6:7]
	s_mov_b64 s[6:7], s[28:29]
	s_waitcnt lgkmcnt(0)
	v_mov_b32_e32 v0, v230
	v_mov_b32_e32 v8, v230
	s_barrier
	s_nop 0
	s_nop 0
	s_nop 0
	s_nop 0
	s_nop 0
	s_nop 0
	s_nop 0
	s_nop 0
	s_nop 0
	s_nop 0
	s_nop 0
	s_nop 0
	s_nop 0
	s_nop 0
	s_and_b64 vcc, exec, s[4:5]
	v_readfirstlane_b32 s1, v8
	s_cbranch_vccnz .LBB0_844
	s_ashr_i32 s3, s2, 31
	s_load_dwordx2 s[4:5], s[6:7], 0xe0
	s_lshr_b32 s6, s3, 29
	s_add_i32 s9, s2, s6
	s_and_b32 s6, s9, -8
	s_sub_i32 s10, s2, s6
	s_cmp_gt_i32 s10, -1
	s_cbranch_scc0 .LBB0_817
	s_lshl_b32 s8, s10, 7
	s_cbranch_execz .LBB0_818
	s_branch .LBB0_819
